# v6 + attention tile loops (FoX, NSA selected/window): serialized ds_read->lgkmcnt(0)->MFMA chains replaced by 3-6 deep fragment prefetch with counted lgkmcnt waits
# speedup vs baseline: 1.0070x; 1.0070x over previous
.LBB0_601:
	s_lshl_b32 s70, 1, s87
	v_and_b32_e32 v2, s70, v178
	v_cmp_ne_u32_e32 vcc, 0, v2
	s_cbranch_vccz .LBB0_607
	v_mov_b32_e32 v2, v170
	v_add_u32_e32 v8, s75, v171
	v_lshlrev_b32_e32 v2, 4, v2
	v_add_u32_e32 v9, v8, v2
	ds_read_b128 v[192:195], v9
	ds_read_b128 v[196:199], v9 offset:8192
	v_xad_u32 v221, v2, 32, v8
	ds_read_b128 v[200:203], v221
	ds_read_b128 v[204:207], v221 offset:8192
	v_xad_u32 v220, v2, 64, v8
	ds_read_b128 v[208:211], v220
	ds_read_b128 v[212:215], v220 offset:8192
	s_cmp_lg_u32 s87, s73
	s_waitcnt lgkmcnt(5)
	v_mfma_f32_32x32x16_bf16 v[98:113], v[192:195], v[138:141], 0
	v_xad_u32 v221, v2, s89, v8
	ds_read_b128 v[192:195], v221
	s_waitcnt lgkmcnt(5)
	v_mfma_f32_32x32x16_bf16 v[82:97], v[196:199], v[138:141], 0
	ds_read_b128 v[196:199], v221 offset:8192
	s_waitcnt lgkmcnt(5)
	v_mfma_f32_32x32x16_bf16 v[98:113], v[200:203], v[114:117], v[98:113]
	v_xad_u32 v220, v2, s90, v8
	ds_read_b128 v[200:203], v220
	s_waitcnt lgkmcnt(5)
	v_mfma_f32_32x32x16_bf16 v[82:97], v[204:207], v[114:117], v[82:97]
	ds_read_b128 v[204:207], v220 offset:8192
	s_waitcnt lgkmcnt(5)
	v_mfma_f32_32x32x16_bf16 v[98:113], v[208:211], v[118:121], v[98:113]
	v_xad_u32 v221, v2, s91, v8
	ds_read_b128 v[208:211], v221
	s_waitcnt lgkmcnt(5)
	v_mfma_f32_32x32x16_bf16 v[82:97], v[212:215], v[118:121], v[82:97]
	ds_read_b128 v[212:215], v221 offset:8192
	s_waitcnt lgkmcnt(5)
	v_mfma_f32_32x32x16_bf16 v[98:113], v[192:195], v[122:125], v[98:113]
	v_xad_u32 v220, v2, s92, v8
	ds_read_b128 v[192:195], v220
	s_waitcnt lgkmcnt(5)
	v_mfma_f32_32x32x16_bf16 v[82:97], v[196:199], v[122:125], v[82:97]
	ds_read_b128 v[196:199], v220 offset:8192
	s_waitcnt lgkmcnt(5)
	v_mfma_f32_32x32x16_bf16 v[98:113], v[200:203], v[126:129], v[98:113]
	v_xad_u32 v221, v2, s93, v8
	ds_read_b128 v[200:203], v221
	s_waitcnt lgkmcnt(5)
	v_mfma_f32_32x32x16_bf16 v[82:97], v[204:207], v[126:129], v[82:97]
	ds_read_b128 v[204:207], v221 offset:8192
	s_waitcnt lgkmcnt(5)
	v_mfma_f32_32x32x16_bf16 v[98:113], v[208:211], v[130:133], v[98:113]
	s_waitcnt lgkmcnt(4)
	v_mfma_f32_32x32x16_bf16 v[82:97], v[212:215], v[130:133], v[82:97]
	s_waitcnt lgkmcnt(3)
	v_mfma_f32_32x32x16_bf16 v[98:113], v[192:195], v[134:137], v[98:113]
	s_waitcnt lgkmcnt(2)
	v_mfma_f32_32x32x16_bf16 v[82:97], v[196:199], v[134:137], v[82:97]
	s_waitcnt lgkmcnt(1)
	v_mfma_f32_32x32x16_bf16 v[98:113], v[200:203], v[142:145], v[98:113]
	s_waitcnt lgkmcnt(0)
	v_mfma_f32_32x32x16_bf16 v[82:97], v[204:207], v[142:145], v[82:97]
	s_cbranch_scc1 .LBB0_604
	s_nop 7
	v_cndmask_b32_e64 v2, v98, v1, s[4:5]
	v_cndmask_b32_e64 v98, v2, v98, s[6:7]
	s_nop 0
	v_cndmask_b32_e64 v2, v82, v1, s[38:39]
	v_cndmask_b32_e64 v99, v1, v99, s[6:7]
	v_cndmask_b32_e64 v100, v100, v1, s[8:9]
	v_cndmask_b32_e64 v101, v101, v1, s[10:11]
	v_cndmask_b32_e64 v102, v102, v1, s[12:13]
	v_cndmask_b32_e64 v103, v103, v1, s[14:15]
	v_cndmask_b32_e64 v104, v104, v1, s[16:17]
	v_cndmask_b32_e64 v105, v105, v1, s[18:19]
	v_cndmask_b32_e64 v106, v106, v1, s[20:21]
	v_cndmask_b32_e64 v107, v107, v1, s[22:23]
	v_cndmask_b32_e64 v108, v108, v1, s[24:25]
	v_cndmask_b32_e64 v109, v109, v1, s[26:27]
	v_cndmask_b32_e64 v110, v110, v1, s[28:29]
	v_cndmask_b32_e64 v111, v111, v1, s[30:31]
	v_cndmask_b32_e64 v112, v112, v1, s[34:35]
	v_cndmask_b32_e64 v113, v113, v1, s[36:37]
	v_cndmask_b32_e64 v83, v1, v83, s[40:41]
	v_cndmask_b32_e64 v82, v2, v82, s[40:41]
	v_cndmask_b32_e64 v84, v84, v1, s[42:43]
	v_cndmask_b32_e64 v85, v85, v1, s[44:45]
	v_cndmask_b32_e64 v86, v86, v1, s[46:47]
	v_cndmask_b32_e64 v87, v87, v1, s[48:49]
	v_cndmask_b32_e64 v88, v88, v1, s[50:51]
	v_cndmask_b32_e64 v89, v89, v1, s[52:53]
	v_cndmask_b32_e64 v90, v90, v1, s[54:55]
	v_cndmask_b32_e64 v91, v91, v1, s[56:57]
	v_cndmask_b32_e64 v92, v92, v1, s[58:59]
	v_cndmask_b32_e64 v93, v93, v1, s[60:61]
	v_cndmask_b32_e64 v94, v94, v1, s[62:63]
	v_cndmask_b32_e64 v95, v95, v1, s[64:65]
	v_cndmask_b32_e64 v96, v96, v1, s[66:67]
	v_cndmask_b32_e64 v97, v97, v1, s[68:69]

.LBB0_606:
	v_cmp_neq_f32_e32 vcc, s33, v180
	s_nop 1
	v_cndmask_b32_e32 v4, 0, v180, vcc
	v_sub_f32_e32 v2, v2, v4
	v_pk_fma_f32 v[8:9], v[112:113], s[72:73], v[2:3] op_sel_hi:[1,0,0]
	v_pk_fma_f32 v[12:13], v[110:111], s[72:73], v[2:3] op_sel_hi:[1,0,0]
	v_pk_fma_f32 v[14:15], v[108:109], s[72:73], v[2:3] op_sel_hi:[1,0,0]
	v_pk_fma_f32 v[16:17], v[106:107], s[72:73], v[2:3] op_sel_hi:[1,0,0]
	v_pk_fma_f32 v[104:105], v[104:105], s[72:73], v[2:3] op_sel_hi:[1,0,0]
	v_pk_fma_f32 v[102:103], v[102:103], s[72:73], v[2:3] op_sel_hi:[1,0,0]
	v_pk_fma_f32 v[10:11], v[100:101], s[72:73], v[2:3] op_sel_hi:[1,0,0]
	v_pk_fma_f32 v[4:5], v[98:99], s[72:73], v[2:3] op_sel_hi:[1,0,0]
	v_pk_fma_f32 v[96:97], v[96:97], s[72:73], v[2:3] op_sel_hi:[1,0,0]
	v_pk_fma_f32 v[94:95], v[94:95], s[72:73], v[2:3] op_sel_hi:[1,0,0]
	v_pk_fma_f32 v[92:93], v[92:93], s[72:73], v[2:3] op_sel_hi:[1,0,0]
	v_pk_fma_f32 v[90:91], v[90:91], s[72:73], v[2:3] op_sel_hi:[1,0,0]
	v_pk_fma_f32 v[88:89], v[88:89], s[72:73], v[2:3] op_sel_hi:[1,0,0]
	v_pk_fma_f32 v[86:87], v[86:87], s[72:73], v[2:3] op_sel_hi:[1,0,0]
	v_pk_fma_f32 v[84:85], v[84:85], s[72:73], v[2:3] op_sel_hi:[1,0,0]
	v_pk_fma_f32 v[82:83], v[82:83], s[72:73], v[2:3] op_sel_hi:[1,0,0]
	v_exp_f32_e32 v6, v4
	v_exp_f32_e32 v4, v82
	v_exp_f32_e32 v7, v5
	v_exp_f32_e32 v5, v83
	v_exp_f32_e32 v98, v10
	v_exp_f32_e32 v10, v84
	v_exp_f32_e32 v99, v11
	v_exp_f32_e32 v11, v85
	v_exp_f32_e32 v84, v102
	v_exp_f32_e32 v86, v86
	v_exp_f32_e32 v85, v103
	v_exp_f32_e32 v87, v87
	v_exp_f32_e32 v100, v104
	v_exp_f32_e32 v88, v88
	v_exp_f32_e32 v101, v105
	v_exp_f32_e32 v89, v89
	v_exp_f32_e32 v16, v16
	v_exp_f32_e32 v90, v90
	v_exp_f32_e32 v17, v17
	v_exp_f32_e32 v91, v91
	v_exp_f32_e32 v14, v14
	v_exp_f32_e32 v92, v92
	v_exp_f32_e32 v15, v15
	v_exp_f32_e32 v93, v93
	v_exp_f32_e32 v102, v12
	v_exp_f32_e32 v94, v94
	v_exp_f32_e32 v103, v13
	v_exp_f32_e32 v95, v95
	v_exp_f32_e32 v8, v8
	v_exp_f32_e32 v96, v96
	v_exp_f32_e32 v9, v9
	v_exp_f32_e32 v97, v97
	v_pk_add_f32 v[12:13], v[16:17], v[90:91]
	v_pk_add_f32 v[82:83], v[14:15], v[92:93]
	v_pk_add_f32 v[104:105], v[98:99], v[10:11]
	v_pk_add_f32 v[106:107], v[8:9], v[96:97]
	v_pk_add_f32 v[108:109], v[100:101], v[88:89]
	v_pk_add_f32 v[110:111], v[102:103], v[94:95]
	v_pk_add_f32 v[112:113], v[84:85], v[86:87]
	v_pk_add_f32 v[182:183], v[6:7], v[4:5]
	v_pk_add_f32 v[110:111], v[112:113], v[110:111]
	v_pk_add_f32 v[106:107], v[108:109], v[106:107]
	v_pk_add_f32 v[82:83], v[104:105], v[82:83]
	v_pk_add_f32 v[12:13], v[182:183], v[12:13]
	v_pk_add_f32 v[82:83], v[82:83], v[106:107]
	v_pk_add_f32 v[12:13], v[12:13], v[110:111]
	v_cvt_pk_bf16_f32 v84, v84, v85
	v_pk_add_f32 v[12:13], v[12:13], v[82:83]
	v_cvt_pk_bf16_f32 v82, v6, v7
	v_add_f32_e32 v2, v12, v13
	v_add_f32_e32 v179, v179, v2
	v_mov_b32_e32 v2, v173
	v_cvt_pk_bf16_f32 v12, v16, v17
	v_add_u32_e32 v16, s75, v174
	v_lshlrev_b32_e32 v2, 4, v2
	v_add_u32_e32 v17, v16, v2
	v_cvt_pk_bf16_f32 v13, v14, v15
	v_cvt_pk_bf16_f32 v15, v8, v9
	v_cvt_pk_bf16_f32 v9, v10, v11
	v_cvt_pk_bf16_f32 v10, v86, v87
	v_cvt_pk_bf16_f32 v11, v88, v89
	ds_read_b128 v[192:195], v17 offset:16384
	ds_read_b128 v[196:199], v17 offset:20480
	ds_read_b128 v[200:203], v17 offset:24576
	ds_read_b128 v[204:207], v17 offset:28672
	v_xad_u32 v220, v2, 32, v16
	ds_read_b128 v[208:211], v220 offset:16384
	ds_read_b128 v[212:215], v220 offset:20480
	v_cvt_pk_bf16_f32 v83, v98, v99
	v_cvt_pk_bf16_f32 v85, v100, v101
	v_cvt_pk_bf16_f32 v14, v102, v103
	v_cvt_pk_bf16_f32 v8, v4, v5
	s_waitcnt lgkmcnt(5)
	s_nop 0
	v_mfma_f32_32x32x16_bf16 v[66:81], v[192:195], v[82:85], v[66:81]
	ds_read_b128 v[192:195], v220 offset:24576
	v_cvt_pk_bf16_f32 v4, v90, v91
	v_cvt_pk_bf16_f32 v5, v92, v93
	v_cvt_pk_bf16_f32 v6, v94, v95
	v_cvt_pk_bf16_f32 v7, v96, v97
	s_waitcnt lgkmcnt(5)
	s_nop 0
	v_mfma_f32_32x32x16_bf16 v[50:65], v[196:199], v[82:85], v[50:65]
	ds_read_b128 v[196:199], v220 offset:28672
	s_waitcnt lgkmcnt(5)
	v_mfma_f32_32x32x16_bf16 v[34:49], v[200:203], v[82:85], v[34:49]
	v_xad_u32 v221, v2, 64, v16
	ds_read_b128 v[200:203], v221 offset:16384
	s_waitcnt lgkmcnt(5)
	v_mfma_f32_32x32x16_bf16 v[18:33], v[204:207], v[82:85], v[18:33]
	ds_read_b128 v[204:207], v221 offset:20480
	s_waitcnt lgkmcnt(5)
	v_mfma_f32_32x32x16_bf16 v[66:81], v[208:211], v[12:15], v[66:81]
	ds_read_b128 v[208:211], v221 offset:24576
	s_waitcnt lgkmcnt(5)
	v_mfma_f32_32x32x16_bf16 v[50:65], v[212:215], v[12:15], v[50:65]
	ds_read_b128 v[212:215], v221 offset:28672
	s_waitcnt lgkmcnt(5)
	v_mfma_f32_32x32x16_bf16 v[34:49], v[192:195], v[12:15], v[34:49]
	v_xad_u32 v191, v2, s89, v16
	ds_read_b128 v[192:195], v191 offset:16384
	s_waitcnt lgkmcnt(5)
	v_mfma_f32_32x32x16_bf16 v[18:33], v[196:199], v[12:15], v[18:33]
	ds_read_b128 v[196:199], v191 offset:20480
	s_waitcnt lgkmcnt(5)
	v_mfma_f32_32x32x16_bf16 v[66:81], v[200:203], v[8:11], v[66:81]
	ds_read_b128 v[200:203], v191 offset:24576
	s_waitcnt lgkmcnt(5)
	v_mfma_f32_32x32x16_bf16 v[50:65], v[204:207], v[8:11], v[50:65]
	ds_read_b128 v[204:207], v191 offset:28672
	s_waitcnt lgkmcnt(5)
	v_mfma_f32_32x32x16_bf16 v[34:49], v[208:211], v[8:11], v[34:49]
	s_waitcnt lgkmcnt(4)
	v_mfma_f32_32x32x16_bf16 v[18:33], v[212:215], v[8:11], v[18:33]
	s_waitcnt lgkmcnt(3)
	v_mfma_f32_32x32x16_bf16 v[66:81], v[192:195], v[4:7], v[66:81]
	s_waitcnt lgkmcnt(2)
	v_mfma_f32_32x32x16_bf16 v[50:65], v[196:199], v[4:7], v[50:65]
	s_waitcnt lgkmcnt(1)
	v_mfma_f32_32x32x16_bf16 v[34:49], v[200:203], v[4:7], v[34:49]
	s_waitcnt lgkmcnt(0)
	v_mfma_f32_32x32x16_bf16 v[18:33], v[204:207], v[4:7], v[18:33]

.LBB0_611:
	v_sub_f32_e32 v101, 0, v108
	v_cmp_neq_f32_e32 vcc, s33, v108
	s_add_i32 s10, s10, 1
	s_add_i32 s4, s4, 64
	v_cndmask_b32_e32 v110, 0, v101, vcc
	v_pk_fma_f32 v[98:99], v[98:99], s[72:73], v[110:111] op_sel_hi:[1,0,0]
	v_pk_fma_f32 v[94:95], v[94:95], s[72:73], v[110:111] op_sel_hi:[1,0,0]
	v_pk_fma_f32 v[90:91], v[90:91], s[72:73], v[110:111] op_sel_hi:[1,0,0]
	v_pk_fma_f32 v[88:89], v[88:89], s[72:73], v[110:111] op_sel_hi:[1,0,0]
	v_pk_fma_f32 v[86:87], v[86:87], s[72:73], v[110:111] op_sel_hi:[1,0,0]
	v_pk_fma_f32 v[84:85], v[84:85], s[72:73], v[110:111] op_sel_hi:[1,0,0]
	v_pk_fma_f32 v[82:83], v[82:83], s[72:73], v[110:111] op_sel_hi:[1,0,0]
	v_pk_fma_f32 v[78:79], v[78:79], s[72:73], v[110:111] op_sel_hi:[1,0,0]
	v_pk_fma_f32 v[112:113], v[74:75], s[72:73], v[110:111] op_sel_hi:[1,0,0]
	v_pk_fma_f32 v[72:73], v[72:73], s[72:73], v[110:111] op_sel_hi:[1,0,0]
	v_pk_fma_f32 v[74:75], v[70:71], s[72:73], v[110:111] op_sel_hi:[1,0,0]
	v_pk_fma_f32 v[96:97], v[96:97], s[72:73], v[110:111] op_sel_hi:[1,0,0]
	v_pk_fma_f32 v[92:93], v[92:93], s[72:73], v[110:111] op_sel_hi:[1,0,0]
	v_pk_fma_f32 v[80:81], v[80:81], s[72:73], v[110:111] op_sel_hi:[1,0,0]
	v_pk_fma_f32 v[76:77], v[76:77], s[72:73], v[110:111] op_sel_hi:[1,0,0]
	v_pk_fma_f32 v[68:69], v[68:69], s[72:73], v[110:111] op_sel_hi:[1,0,0]
	v_exp_f32_e32 v70, v84
	v_exp_f32_e32 v71, v85
	v_exp_f32_e32 v84, v86
	v_exp_f32_e32 v74, v74
	v_exp_f32_e32 v85, v87
	v_exp_f32_e32 v75, v75
	v_exp_f32_e32 v86, v88
	v_exp_f32_e32 v88, v72
	v_exp_f32_e32 v87, v89
	v_exp_f32_e32 v89, v73
	v_exp_f32_e32 v72, v90
	v_exp_f32_e32 v90, v112
	v_exp_f32_e32 v73, v91
	v_exp_f32_e32 v91, v113
	v_exp_f32_e32 v94, v94
	v_exp_f32_e32 v112, v78
	v_exp_f32_e32 v95, v95
	v_exp_f32_e32 v113, v79
	v_exp_f32_e32 v98, v98
	v_exp_f32_e32 v158, v82
	v_exp_f32_e32 v99, v99
	v_exp_f32_e32 v159, v83
	v_exp_f32_e32 v68, v68
	v_exp_f32_e32 v69, v69
	v_exp_f32_e32 v92, v92
	v_exp_f32_e32 v110, v76
	v_exp_f32_e32 v93, v93
	v_exp_f32_e32 v111, v77
	v_exp_f32_e32 v78, v96
	v_exp_f32_e32 v96, v80
	v_exp_f32_e32 v79, v97
	v_exp_f32_e32 v97, v81
	v_pk_add_f32 v[76:77], v[94:95], v[112:113]
	v_pk_add_f32 v[80:81], v[84:85], v[74:75]
	v_pk_add_f32 v[82:83], v[98:99], v[158:159]
	v_pk_add_f32 v[166:167], v[72:73], v[90:91]
	v_pk_add_f32 v[176:177], v[92:93], v[110:111]
	v_pk_add_f32 v[178:179], v[70:71], v[68:69]
	v_pk_add_f32 v[180:181], v[78:79], v[96:97]
	v_pk_add_f32 v[182:183], v[86:87], v[88:89]
	v_pk_add_f32 v[82:83], v[166:167], v[82:83]
	v_pk_add_f32 v[76:77], v[80:81], v[76:77]
	v_mov_b32_e32 v101, v173
	v_pk_add_f32 v[180:181], v[182:183], v[180:181]
	v_pk_add_f32 v[176:177], v[178:179], v[176:177]
	v_pk_add_f32 v[76:77], v[76:77], v[82:83]
	v_cvt_pk_bf16_f32 v83, v72, v73
	v_cvt_pk_bf16_f32 v73, v74, v75
	v_cvt_pk_bf16_f32 v74, v88, v89
	v_add_u32_e32 v88, s11, v174
	v_lshlrev_b32_e32 v89, 4, v101
	v_pk_add_f32 v[80:81], v[176:177], v[180:181]
	v_cvt_pk_bf16_f32 v75, v90, v91
	v_add_u32_e32 v90, v88, v89
	v_pk_add_f32 v[76:77], v[80:81], v[76:77]
	v_cvt_pk_bf16_f32 v81, v84, v85
	v_cvt_pk_bf16_f32 v82, v86, v87
	ds_read_b128 v[192:195], v90 offset:16384
	ds_read_b128 v[196:199], v90 offset:20480
	ds_read_b128 v[200:203], v90 offset:24576
	ds_read_b128 v[204:207], v90 offset:28672
	v_xad_u32 v220, v89, 32, v88
	ds_read_b128 v[208:211], v220 offset:16384
	ds_read_b128 v[212:215], v220 offset:20480
	v_cvt_pk_bf16_f32 v80, v70, v71
	v_add_f32_e32 v76, v76, v77
	v_add_f32_e32 v106, v106, v76
	s_waitcnt lgkmcnt(5)
	s_nop 0
	v_mfma_f32_32x32x16_bf16 v[52:67], v[192:195], v[80:83], v[52:67]
	ds_read_b128 v[192:195], v220 offset:24576
	v_cvt_pk_bf16_f32 v76, v92, v93
	v_cvt_pk_bf16_f32 v77, v94, v95
	v_cvt_pk_bf16_f32 v78, v78, v79
	v_cvt_pk_bf16_f32 v79, v98, v99
	v_cvt_pk_bf16_f32 v72, v68, v69
	v_cvt_pk_bf16_f32 v68, v110, v111
	s_waitcnt lgkmcnt(5)
	s_nop 0
	v_mfma_f32_32x32x16_bf16 v[36:51], v[196:199], v[80:83], v[36:51]
	ds_read_b128 v[196:199], v220 offset:28672
	v_cvt_pk_bf16_f32 v69, v112, v113
	v_cvt_pk_bf16_f32 v70, v96, v97
	v_cvt_pk_bf16_f32 v71, v158, v159
	s_xor_b32 s11, s11, 0x8000
	v_lshl_add_u64 v[102:103], v[102:103], 0, s[16:17]
	v_lshl_add_u64 v[104:105], v[104:105], 0, s[16:17]
	s_waitcnt lgkmcnt(5)
	s_nop 0
	v_mfma_f32_32x32x16_bf16 v[20:35], v[200:203], v[80:83], v[20:35]
	v_xad_u32 v221, v89, 64, v88
	ds_read_b128 v[200:203], v221 offset:16384
	s_and_b64 vcc, exec, s[6:7]
	s_waitcnt lgkmcnt(5)
	v_mfma_f32_32x32x16_bf16 v[4:19], v[204:207], v[80:83], v[4:19]
	ds_read_b128 v[204:207], v221 offset:20480
	s_waitcnt lgkmcnt(5)
	v_mfma_f32_32x32x16_bf16 v[52:67], v[208:211], v[76:79], v[52:67]
	ds_read_b128 v[208:211], v221 offset:24576
	s_waitcnt lgkmcnt(5)
	v_mfma_f32_32x32x16_bf16 v[36:51], v[212:215], v[76:79], v[36:51]
	ds_read_b128 v[212:215], v221 offset:28672
	s_waitcnt lgkmcnt(5)
	v_mfma_f32_32x32x16_bf16 v[20:35], v[192:195], v[76:79], v[20:35]
	v_xad_u32 v191, v89, s89, v88
	ds_read_b128 v[192:195], v191 offset:16384
	s_waitcnt lgkmcnt(5)
	v_mfma_f32_32x32x16_bf16 v[4:19], v[196:199], v[76:79], v[4:19]
	ds_read_b128 v[196:199], v191 offset:20480
	s_waitcnt lgkmcnt(5)
	v_mfma_f32_32x32x16_bf16 v[52:67], v[200:203], v[72:75], v[52:67]
	ds_read_b128 v[200:203], v191 offset:24576
	s_waitcnt lgkmcnt(5)
	v_mfma_f32_32x32x16_bf16 v[36:51], v[204:207], v[72:75], v[36:51]
	ds_read_b128 v[204:207], v191 offset:28672
	s_waitcnt lgkmcnt(5)
	v_mfma_f32_32x32x16_bf16 v[20:35], v[208:211], v[72:75], v[20:35]
	s_waitcnt lgkmcnt(4)
	v_mfma_f32_32x32x16_bf16 v[4:19], v[212:215], v[72:75], v[4:19]
	s_waitcnt lgkmcnt(3)
	v_mfma_f32_32x32x16_bf16 v[52:67], v[192:195], v[68:71], v[52:67]
	s_waitcnt lgkmcnt(2)
	v_mfma_f32_32x32x16_bf16 v[36:51], v[196:199], v[68:71], v[36:51]
	s_waitcnt lgkmcnt(1)
	v_mfma_f32_32x32x16_bf16 v[20:35], v[200:203], v[68:71], v[20:35]
	s_waitcnt lgkmcnt(0)
	v_mfma_f32_32x32x16_bf16 v[4:19], v[204:207], v[68:71], v[4:19]
	s_cbranch_vccnz .LBB0_538

.LBB0_614:
	v_mov_b32_e32 v68, v170
	v_add_u32_e32 v101, s11, v171
	v_lshlrev_b32_e32 v109, 4, v68
	v_add_u32_e32 v72, v101, v109
	ds_read_b128 v[192:195], v72
	ds_read_b128 v[196:199], v72 offset:8192
	v_xad_u32 v221, v109, 32, v101
	ds_read_b128 v[200:203], v221
	ds_read_b128 v[204:207], v221 offset:8192
	v_xad_u32 v220, v109, 64, v101
	ds_read_b128 v[208:211], v220
	ds_read_b128 v[212:215], v220 offset:8192
	s_cmp_eq_u32 s73, s10
	s_cselect_b64 s[0:1], -1, 0
	s_cmp_eq_u32 s9, s10
	s_cselect_b64 s[12:13], -1, 0
	s_or_b64 s[0:1], s[0:1], s[12:13]
	s_andn2_b64 vcc, exec, s[0:1]
	s_waitcnt lgkmcnt(5)
	v_mfma_f32_32x32x16_bf16 v[84:99], v[192:195], v[138:141], 0
	v_xad_u32 v221, v109, s89, v101
	ds_read_b128 v[192:195], v221
	s_waitcnt lgkmcnt(5)
	v_mfma_f32_32x32x16_bf16 v[68:83], v[196:199], v[138:141], 0
	ds_read_b128 v[196:199], v221 offset:8192
	s_waitcnt lgkmcnt(5)
	v_mfma_f32_32x32x16_bf16 v[84:99], v[200:203], v[114:117], v[84:99]
	v_xad_u32 v220, v109, s90, v101
	ds_read_b128 v[200:203], v220
	s_waitcnt lgkmcnt(5)
	v_mfma_f32_32x32x16_bf16 v[68:83], v[204:207], v[114:117], v[68:83]
	ds_read_b128 v[204:207], v220 offset:8192
	s_waitcnt lgkmcnt(5)
	v_mfma_f32_32x32x16_bf16 v[84:99], v[208:211], v[118:121], v[84:99]
	v_xad_u32 v221, v109, s91, v101
	ds_read_b128 v[208:211], v221
	s_waitcnt lgkmcnt(5)
	v_mfma_f32_32x32x16_bf16 v[68:83], v[212:215], v[118:121], v[68:83]
	ds_read_b128 v[212:215], v221 offset:8192
	s_waitcnt lgkmcnt(5)
	v_mfma_f32_32x32x16_bf16 v[84:99], v[192:195], v[122:125], v[84:99]
	v_xad_u32 v220, v109, s92, v101
	ds_read_b128 v[192:195], v220
	s_waitcnt lgkmcnt(5)
	v_mfma_f32_32x32x16_bf16 v[68:83], v[196:199], v[122:125], v[68:83]
	ds_read_b128 v[196:199], v220 offset:8192
	s_waitcnt lgkmcnt(5)
	v_mfma_f32_32x32x16_bf16 v[84:99], v[200:203], v[126:129], v[84:99]
	v_xad_u32 v221, v109, s14, v101
	ds_read_b128 v[200:203], v221
	s_waitcnt lgkmcnt(5)
	v_mfma_f32_32x32x16_bf16 v[68:83], v[204:207], v[126:129], v[68:83]
	ds_read_b128 v[204:207], v221 offset:8192
	s_waitcnt lgkmcnt(5)
	v_mfma_f32_32x32x16_bf16 v[84:99], v[208:211], v[130:133], v[84:99]
	s_waitcnt lgkmcnt(4)
	v_mfma_f32_32x32x16_bf16 v[68:83], v[212:215], v[130:133], v[68:83]
	s_waitcnt lgkmcnt(3)
	v_mfma_f32_32x32x16_bf16 v[84:99], v[192:195], v[134:137], v[84:99]
	s_waitcnt lgkmcnt(2)
	v_mfma_f32_32x32x16_bf16 v[68:83], v[196:199], v[134:137], v[68:83]
	s_waitcnt lgkmcnt(1)
	v_mfma_f32_32x32x16_bf16 v[84:99], v[200:203], v[142:145], v[84:99]
	s_waitcnt lgkmcnt(0)
	v_mfma_f32_32x32x16_bf16 v[68:83], v[204:207], v[142:145], v[68:83]
	s_cbranch_vccnz .LBB0_616
	v_add_u32_e32 v101, s4, v148
	v_subrev_u32_e32 v109, 64, v101
	v_cmp_gt_i32_e32 vcc, v109, v169
	v_cmp_lt_i32_e64 s[0:1], v109, v107
	s_or_b64 vcc, vcc, s[0:1]
	v_subrev_u32_e32 v110, 63, v101
	s_nop 1
	v_cndmask_b32_e32 v84, v84, v1, vcc
	v_cmp_ge_i32_e32 vcc, v109, v169
	v_cmp_lt_i32_e64 s[0:1], v110, v107
	s_or_b64 vcc, vcc, s[0:1]
	v_subrev_u32_e32 v109, 62, v101
	v_cndmask_b32_e32 v85, v85, v1, vcc
	v_cmp_gt_i32_e32 vcc, v109, v169
	v_cmp_lt_i32_e64 s[0:1], v109, v107
	s_or_b64 vcc, vcc, s[0:1]
	v_subrev_u32_e32 v109, 61, v101
	v_cndmask_b32_e32 v86, v86, v1, vcc
	v_cmp_gt_i32_e32 vcc, v109, v169
	v_cmp_lt_i32_e64 s[0:1], v109, v107
	s_or_b64 vcc, vcc, s[0:1]
	v_subrev_u32_e32 v109, 56, v101
	v_cndmask_b32_e32 v87, v87, v1, vcc
	v_cmp_gt_i32_e32 vcc, v109, v169
	v_cmp_lt_i32_e64 s[0:1], v109, v107
	s_or_b64 vcc, vcc, s[0:1]
	v_subrev_u32_e32 v109, 55, v101
	v_cndmask_b32_e32 v88, v88, v1, vcc
	v_cmp_gt_i32_e32 vcc, v109, v169
	v_cmp_lt_i32_e64 s[0:1], v109, v107
	s_or_b64 vcc, vcc, s[0:1]
	v_subrev_u32_e32 v109, 54, v101
	v_cndmask_b32_e32 v89, v89, v1, vcc
	v_cmp_gt_i32_e32 vcc, v109, v169
	v_cmp_lt_i32_e64 s[0:1], v109, v107
	s_or_b64 vcc, vcc, s[0:1]
	v_subrev_u32_e32 v109, 53, v101
	v_cndmask_b32_e32 v90, v90, v1, vcc
	v_cmp_gt_i32_e32 vcc, v109, v169
	v_cmp_lt_i32_e64 s[0:1], v109, v107
	s_or_b64 vcc, vcc, s[0:1]
	v_subrev_u32_e32 v109, 48, v101
	v_cndmask_b32_e32 v91, v91, v1, vcc
	v_cmp_gt_i32_e32 vcc, v109, v169
	v_cmp_lt_i32_e64 s[0:1], v109, v107
	s_or_b64 vcc, vcc, s[0:1]
	v_subrev_u32_e32 v109, 47, v101
	v_cndmask_b32_e32 v92, v92, v1, vcc
	v_cmp_gt_i32_e32 vcc, v109, v169
	v_cmp_lt_i32_e64 s[0:1], v109, v107
	s_or_b64 vcc, vcc, s[0:1]
	v_subrev_u32_e32 v109, 46, v101
	v_cndmask_b32_e32 v93, v93, v1, vcc
	v_cmp_gt_i32_e32 vcc, v109, v169
	v_cmp_lt_i32_e64 s[0:1], v109, v107
	s_or_b64 vcc, vcc, s[0:1]
	v_subrev_u32_e32 v109, 45, v101
	v_cndmask_b32_e32 v94, v94, v1, vcc
	v_cmp_gt_i32_e32 vcc, v109, v169
	v_cmp_lt_i32_e64 s[0:1], v109, v107
	s_or_b64 vcc, vcc, s[0:1]
	v_subrev_u32_e32 v109, 40, v101
	v_cndmask_b32_e32 v95, v95, v1, vcc
	v_cmp_gt_i32_e32 vcc, v109, v169
	v_cmp_lt_i32_e64 s[0:1], v109, v107
	s_or_b64 vcc, vcc, s[0:1]
	v_subrev_u32_e32 v109, 39, v101
	v_cndmask_b32_e32 v96, v96, v1, vcc
	v_cmp_gt_i32_e32 vcc, v109, v169
	v_cmp_lt_i32_e64 s[0:1], v109, v107
	s_or_b64 vcc, vcc, s[0:1]
	v_subrev_u32_e32 v109, 38, v101
	v_cndmask_b32_e32 v97, v97, v1, vcc
	v_cmp_gt_i32_e32 vcc, v109, v169
	v_cmp_lt_i32_e64 s[0:1], v109, v107
	s_or_b64 vcc, vcc, s[0:1]
	v_subrev_u32_e32 v109, 37, v101
	v_cndmask_b32_e32 v98, v98, v1, vcc
	v_cmp_gt_i32_e32 vcc, v109, v169
	v_cmp_lt_i32_e64 s[0:1], v109, v107
	s_or_b64 vcc, vcc, s[0:1]
	v_subrev_u32_e32 v109, 32, v101
	v_cndmask_b32_e32 v99, v99, v1, vcc
	v_cmp_gt_i32_e32 vcc, v109, v169
	v_cmp_lt_i32_e64 s[0:1], v109, v107
	s_or_b64 vcc, vcc, s[0:1]
	v_subrev_u32_e32 v110, 31, v101
	v_cndmask_b32_e32 v68, v68, v1, vcc
	v_cmp_ge_i32_e32 vcc, v109, v169
	v_cmp_lt_i32_e64 s[0:1], v110, v107
	s_or_b64 vcc, vcc, s[0:1]
	v_subrev_u32_e32 v109, 30, v101
	v_cndmask_b32_e32 v69, v69, v1, vcc
	v_cmp_gt_i32_e32 vcc, v109, v169
	v_cmp_lt_i32_e64 s[0:1], v109, v107
	s_or_b64 vcc, vcc, s[0:1]
	v_subrev_u32_e32 v109, 29, v101
	v_cndmask_b32_e32 v70, v70, v1, vcc
	v_cmp_gt_i32_e32 vcc, v109, v169
	v_cmp_lt_i32_e64 s[0:1], v109, v107
	s_or_b64 vcc, vcc, s[0:1]
	v_subrev_u32_e32 v109, 24, v101
	v_cndmask_b32_e32 v71, v71, v1, vcc
	v_cmp_gt_i32_e32 vcc, v109, v169
	v_cmp_lt_i32_e64 s[0:1], v109, v107
	s_or_b64 vcc, vcc, s[0:1]
	v_subrev_u32_e32 v109, 23, v101
	v_cndmask_b32_e32 v72, v72, v1, vcc
	v_cmp_gt_i32_e32 vcc, v109, v169
	v_cmp_lt_i32_e64 s[0:1], v109, v107
	s_or_b64 vcc, vcc, s[0:1]
	v_subrev_u32_e32 v109, 22, v101
	v_cndmask_b32_e32 v73, v73, v1, vcc
	v_cmp_gt_i32_e32 vcc, v109, v169
	v_cmp_lt_i32_e64 s[0:1], v109, v107
	s_or_b64 vcc, vcc, s[0:1]
	v_subrev_u32_e32 v109, 21, v101
	v_cndmask_b32_e32 v74, v74, v1, vcc
	v_cmp_gt_i32_e32 vcc, v109, v169
	v_cmp_lt_i32_e64 s[0:1], v109, v107
	s_or_b64 vcc, vcc, s[0:1]
	v_add_u32_e32 v109, -16, v101
	v_cndmask_b32_e32 v75, v75, v1, vcc
	v_cmp_gt_i32_e32 vcc, v109, v169
	v_cmp_lt_i32_e64 s[0:1], v109, v107
	s_or_b64 vcc, vcc, s[0:1]
	v_add_u32_e32 v109, -15, v101
	v_cndmask_b32_e32 v76, v76, v1, vcc
	v_cmp_gt_i32_e32 vcc, v109, v169
	v_cmp_lt_i32_e64 s[0:1], v109, v107
	s_or_b64 vcc, vcc, s[0:1]
	v_add_u32_e32 v109, -14, v101
	v_cndmask_b32_e32 v77, v77, v1, vcc
	v_cmp_gt_i32_e32 vcc, v109, v169
	v_cmp_lt_i32_e64 s[0:1], v109, v107
	s_or_b64 vcc, vcc, s[0:1]
	v_add_u32_e32 v109, -13, v101
	v_cndmask_b32_e32 v78, v78, v1, vcc
	v_cmp_gt_i32_e32 vcc, v109, v169
	v_cmp_lt_i32_e64 s[0:1], v109, v107
	s_or_b64 vcc, vcc, s[0:1]
	v_add_u32_e32 v109, -8, v101
	v_cndmask_b32_e32 v79, v79, v1, vcc
	v_cmp_gt_i32_e32 vcc, v109, v169
	v_cmp_lt_i32_e64 s[0:1], v109, v107
	s_or_b64 vcc, vcc, s[0:1]
	v_add_u32_e32 v109, -7, v101
	v_cndmask_b32_e32 v80, v80, v1, vcc
	v_cmp_gt_i32_e32 vcc, v109, v169
	v_cmp_lt_i32_e64 s[0:1], v109, v107
	s_or_b64 vcc, vcc, s[0:1]
	v_add_u32_e32 v109, -6, v101
	v_cndmask_b32_e32 v81, v81, v1, vcc
	v_cmp_gt_i32_e32 vcc, v109, v169
	v_cmp_lt_i32_e64 s[0:1], v109, v107
	s_or_b64 vcc, vcc, s[0:1]
	v_add_u32_e32 v101, -5, v101
	v_cndmask_b32_e32 v82, v82, v1, vcc
	v_cmp_gt_i32_e32 vcc, v101, v169
	v_cmp_lt_i32_e64 s[0:1], v101, v107
	s_or_b64 vcc, vcc, s[0:1]
	v_cndmask_b32_e32 v83, v83, v1, vcc

.LBB0_1489:
	s_cmp_gt_i32 s56, s29
	s_cbranch_scc1 .LBB0_1478
	s_lshl_b32 s8, s58, 15
	v_mov_b32_e32 v2, v234
	v_add_u32_e32 v10, s8, v235
	v_lshlrev_b32_e32 v11, 4, v2
	v_add_u32_e32 v6, v10, v11
	ds_read_b128 v[12:15], v6
	ds_read_b128 v[16:19], v6 offset:8192
	v_xad_u32 v28, v11, 32, v10
	ds_read_b128 v[20:23], v28
	ds_read_b128 v[24:27], v28 offset:8192
	v_xad_u32 v29, v11, 64, v10
	ds_read_b128 v[2:5], v29
	ds_read_b128 v[6:9], v29 offset:8192
	s_lshl_b32 s26, s58, 8
	s_add_i32 s59, s26, 0x18000
	s_add_i32 s60, s56, 63
	s_mov_b64 s[26:27], -1
	s_cmp_gt_i32 s60, s55
	v_add_u32_e32 v187, s59, v236
	s_waitcnt lgkmcnt(4)
	v_mfma_f32_32x32x16_bf16 v[114:129], v[12:15], v[154:157], 0
	v_mfma_f32_32x32x16_bf16 v[98:113], v[16:19], v[154:157], 0
	v_xad_u32 v28, v11, s44, v10
	ds_read_b128 v[12:15], v28
	ds_read_b128 v[16:19], v28 offset:8192
	s_waitcnt lgkmcnt(4)
	v_mfma_f32_32x32x16_bf16 v[114:129], v[20:23], v[130:133], v[114:129]
	v_mfma_f32_32x32x16_bf16 v[98:113], v[24:27], v[130:133], v[98:113]
	v_xad_u32 v29, v11, s43, v10
	ds_read_b128 v[20:23], v29
	ds_read_b128 v[24:27], v29 offset:8192
	s_waitcnt lgkmcnt(4)
	v_mfma_f32_32x32x16_bf16 v[114:129], v[2:5], v[134:137], v[114:129]
	v_mfma_f32_32x32x16_bf16 v[98:113], v[6:9], v[134:137], v[98:113]
	v_xad_u32 v28, v11, s45, v10
	ds_read_b128 v[2:5], v28
	ds_read_b128 v[6:9], v28 offset:8192
	s_waitcnt lgkmcnt(4)
	v_mfma_f32_32x32x16_bf16 v[114:129], v[12:15], v[138:141], v[114:129]
	v_mfma_f32_32x32x16_bf16 v[98:113], v[16:19], v[138:141], v[98:113]
	v_xad_u32 v29, v11, s46, v10
	ds_read_b128 v[12:15], v29
	ds_read_b128 v[16:19], v29 offset:8192
	s_waitcnt lgkmcnt(4)
	v_mfma_f32_32x32x16_bf16 v[114:129], v[20:23], v[142:145], v[114:129]
	v_mfma_f32_32x32x16_bf16 v[98:113], v[24:27], v[142:145], v[98:113]
	v_xad_u32 v28, v11, s47, v10
	ds_read_b128 v[20:23], v28
	ds_read_b128 v[24:27], v28 offset:8192
	s_waitcnt lgkmcnt(4)
	v_mfma_f32_32x32x16_bf16 v[114:129], v[2:5], v[146:149], v[114:129]
	v_mfma_f32_32x32x16_bf16 v[98:113], v[6:9], v[146:149], v[98:113]
	s_waitcnt lgkmcnt(2)
	v_mfma_f32_32x32x16_bf16 v[114:129], v[12:15], v[150:153], v[114:129]
	v_mfma_f32_32x32x16_bf16 v[98:113], v[16:19], v[150:153], v[98:113]
	s_waitcnt lgkmcnt(0)
	v_mfma_f32_32x32x16_bf16 v[114:129], v[20:23], v[158:161], v[114:129]
	v_mfma_f32_32x32x16_bf16 v[98:113], v[24:27], v[158:161], v[98:113]
	s_cbranch_scc1 .LBB0_1492
	ds_read_b128 v[2:5], v187
	ds_read_b128 v[6:9], v187 offset:32
	ds_read_b128 v[10:13], v187 offset:64
	s_mov_b64 s[26:27], 0
	s_waitcnt lgkmcnt(0)
	s_nop 4
	v_pk_fma_f32 v[2:3], v[114:115], s[18:19], v[2:3] op_sel_hi:[1,0,1]
	v_pk_fma_f32 v[218:219], v[116:117], s[18:19], v[4:5] op_sel_hi:[1,0,1]
	v_max3_f32 v4, v2, s48, v3
	v_pk_fma_f32 v[220:221], v[118:119], s[18:19], v[6:7] op_sel_hi:[1,0,1]
	v_max3_f32 v4, v4, v218, v219
	v_max3_f32 v4, v4, v220, v221
	v_pk_fma_f32 v[228:229], v[120:121], s[18:19], v[8:9] op_sel_hi:[1,0,1]
	v_pk_fma_f32 v[204:205], v[122:123], s[18:19], v[10:11] op_sel_hi:[1,0,1]
	v_max3_f32 v8, v4, v228, v229
	ds_read_b128 v[4:7], v187 offset:96
	v_max3_f32 v8, v8, v204, v205
	v_pk_fma_f32 v[206:207], v[124:125], s[18:19], v[12:13] op_sel_hi:[1,0,1]
	s_nop 0
	v_max3_f32 v12, v8, v206, v207
	ds_read_b128 v[8:11], v187 offset:128
	s_waitcnt lgkmcnt(0)
	v_pk_fma_f32 v[208:209], v[126:127], s[18:19], v[4:5] op_sel_hi:[1,0,1]
	v_pk_fma_f32 v[212:213], v[128:129], s[18:19], v[6:7] op_sel_hi:[1,0,1]
	v_max3_f32 v4, v12, v208, v209
	v_max3_f32 v12, v4, v212, v213
	ds_read_b128 v[4:7], v187 offset:160
	v_pk_fma_f32 v[210:211], v[98:99], s[18:19], v[8:9] op_sel_hi:[1,0,1]
	v_pk_fma_f32 v[214:215], v[100:101], s[18:19], v[10:11] op_sel_hi:[1,0,1]
	v_max3_f32 v8, v12, v210, v211
	v_max3_f32 v12, v8, v214, v215
	ds_read_b128 v[8:11], v187 offset:192
	s_waitcnt lgkmcnt(0)
	v_pk_fma_f32 v[216:217], v[102:103], s[18:19], v[4:5] op_sel_hi:[1,0,1]
	v_pk_fma_f32 v[224:225], v[104:105], s[18:19], v[6:7] op_sel_hi:[1,0,1]
	v_max3_f32 v4, v12, v216, v217
	v_max3_f32 v12, v4, v224, v225
	ds_read_b128 v[4:7], v187 offset:224
	v_pk_fma_f32 v[222:223], v[106:107], s[18:19], v[8:9] op_sel_hi:[1,0,1]
	v_pk_fma_f32 v[226:227], v[108:109], s[18:19], v[10:11] op_sel_hi:[1,0,1]
	v_max3_f32 v8, v12, v222, v223
	v_max3_f32 v8, v8, v226, v227
	s_waitcnt lgkmcnt(0)
	v_pk_fma_f32 v[230:231], v[110:111], s[18:19], v[4:5] op_sel_hi:[1,0,1]
	v_pk_fma_f32 v[232:233], v[112:113], s[18:19], v[6:7] op_sel_hi:[1,0,1]
	v_max3_f32 v4, v8, v230, v231
	v_max3_f32 v241, v4, v232, v233
